# GEMM K-loops trimmed: redundant post-barrier lgkmcnt waits, inner setprio pairs and m0 hazard nops removed (m0 writes hoisted before the address VALU) on top of v36
# baseline (speedup 1.0000x reference)
; #define PG8_STAGE(bufoff, gbase, voff) do { _Pragma("unroll") for (int _i = 0; _i < 2; ++_i) \
;         __builtin_amdgcn_global_load_lds((const unsigned*)((const char*)(gbase) + (voff)[_i]), (PG8_LAS unsigned*)(lds + (bufoff) + ldsw + _i * 8192), 16, 0, 0); } while (0)
; #define PG8_LDA(dst, b, h) do { _Pragma("unroll") for (int m = 0; m < 4; ++m) _Pragma("unroll") for (int k = 0; k < 2; ++k) dst[m][k] = *(const PG8_LAS bf16x8*)(lds + PG8_SA(b, h) + aoff + m * 2048 + k * 1024); } while (0)
; #define PG8_LDB(dst, b, h) do { _Pragma("unroll") for (int n = 0; n < 2; ++n) _Pragma("unroll") for (int k = 0; k < 2; ++k) dst[n][k] = *(const PG8_LAS bf16x8*)(lds + PG8_SB(b, h) + boff + n * 2048 + k * 1024); } while (0)
; #define PG8_MMA(ai, bj, At, Bt) do { __builtin_amdgcn_s_setprio(1); _Pragma("unroll") for (int m = 0; m < 4; ++m) _Pragma("unroll") for (int n = 0; n < 2; ++n) _Pragma("unroll") for (int k = 0; k < 2; ++k) \
;         acc[ai][bj][m][n] = __builtin_amdgcn_mfma_f32_16x16x32_bf16(Bt[n][k], At[m][k], acc[ai][bj][m][n], 0, 0, 0); __builtin_amdgcn_s_setprio(0); } while (0)
; #define PG8_WAIT_V(n) asm volatile("s_waitcnt vmcnt(" #n ")" ::: "memory")
; #define PG8_WAIT_L(n) asm volatile("s_waitcnt lgkmcnt(" #n ")" ::: "memory")
; #define PG8_BAR __builtin_amdgcn_s_barrier()
; #define PG8_SCHED __builtin_amdgcn_sched_barrier(0)
; template <class Epi, class Sched, bool ALIGN_EPI = false, bool SP2 = false>
; __device__ __forceinline__ void gemm_phase(PG8_LAS unsigned char* lds, const Gemm g, const Sched& S, const Epi& E, const int tid_in) {
;     ...
;             PG8_LDB(B0, 0, 0); PG8_LDB(B1, 0, 1); PG8_SCHED; PG8_LDA(At, 0, 0); PG8_STAGE(PG8_SA(1, 1), a1 + hstep, voffA);
;             PG8_WAIT_V(8); PG8_WAIT_L(0); PG8_BAR; PG8_MMA(0, 0, At, B0); PG8_MMA(0, 1, At, B1); PG8_BAR; PG8_SCHED;
;             PG8_LDA(At, 0, 1); PG8_STAGE(PG8_SB(0, 0), b2, voffB); PG8_STAGE(PG8_SB(0, 1), b2 + hstep, voffB); PG8_STAGE(PG8_SA(0, 0), a2, voffA);
;             PG8_WAIT_V(8); PG8_WAIT_L(0); PG8_BAR; PG8_MMA(1, 0, At, B0); PG8_MMA(1, 1, At, B1); PG8_BAR; PG8_SCHED;
.LBB0_42:
	s_add_u32 s10, s4, 0xfffc0080
	s_addc_u32 s11, s5, -1
	s_add_i32 s61, 0, 0x10000
	s_cmp_eq_u32 s60, 12
	s_cselect_b32 s13, s14, s11
	s_cselect_b32 s12, s15, s10
	s_cselect_b32 s11, s23, s59
	s_cselect_b32 s10, s25, s58
	s_add_i32 s64, 0, 0x14000
	s_waitcnt vmcnt(0)
	v_add_u32_e32 v76, s61, v162
	v_add_u32_e32 v160, s64, v162
	ds_read_b128 v[56:59], v76
	ds_read_b128 v[64:67], v76 offset:1024
	ds_read_b128 v[68:71], v76 offset:2048
	ds_read_b128 v[76:79], v76 offset:3072
	ds_read_b128 v[170:173], v160
	ds_read_b128 v[174:177], v160 offset:1024
	ds_read_b128 v[178:181], v160 offset:2048
	ds_read_b128 v[182:185], v160 offset:3072
	v_lshl_add_u64 v[160:161], s[4:5], 0, v[156:157]
	s_add_i32 m0, s48, 0xc000
	ds_read_b128 v[186:189], v168
	ds_read_b128 v[200:203], v168 offset:1024
	ds_read_b128 v[204:207], v168 offset:2048
	ds_read_b128 v[208:211], v168 offset:3072
	ds_read_b128 v[212:215], v168 offset:4096
	ds_read_b128 v[234:237], v168 offset:5120
	ds_read_b128 v[238:241], v168 offset:6144
	ds_read_b128 v[242:245], v168 offset:7168
	global_load_lds_dwordx4 v[160:161], off
	s_add_i32 m0, s48, 0xe000
	v_lshl_add_u64 v[160:161], s[4:5], 0, v[158:159]
	global_load_lds_dwordx4 v[160:161], off
	s_waitcnt vmcnt(8)
	s_waitcnt lgkmcnt(0)
	s_barrier
	s_setprio 1
	v_mfma_f32_16x16x32_bf16 v[140:143], v[56:59], v[186:189], v[140:143]
	v_mfma_f32_16x16x32_bf16 v[136:139], v[68:71], v[186:189], v[136:139]
	v_mfma_f32_16x16x32_bf16 v[124:127], v[56:59], v[204:207], v[124:127]
	v_mfma_f32_16x16x32_bf16 v[120:123], v[68:71], v[204:207], v[120:123]
	v_mfma_f32_16x16x32_bf16 v[108:111], v[56:59], v[212:215], v[108:111]
	v_mfma_f32_16x16x32_bf16 v[104:107], v[68:71], v[212:215], v[104:107]
	v_mfma_f32_16x16x32_bf16 v[92:95], v[56:59], v[238:241], v[92:95]
	v_mfma_f32_16x16x32_bf16 v[88:91], v[68:71], v[238:241], v[88:91]
	v_mfma_f32_16x16x32_bf16 v[140:143], v[64:67], v[200:203], v[140:143]
	v_mfma_f32_16x16x32_bf16 v[136:139], v[76:79], v[200:203], v[136:139]
	v_mfma_f32_16x16x32_bf16 v[124:127], v[64:67], v[208:211], v[124:127]
	v_mfma_f32_16x16x32_bf16 v[120:123], v[76:79], v[208:211], v[120:123]
	v_mfma_f32_16x16x32_bf16 v[108:111], v[64:67], v[234:237], v[108:111]
	v_mfma_f32_16x16x32_bf16 v[104:107], v[76:79], v[234:237], v[104:107]
	v_mfma_f32_16x16x32_bf16 v[92:95], v[64:67], v[242:245], v[92:95]
	v_mfma_f32_16x16x32_bf16 v[88:91], v[76:79], v[242:245], v[88:91]
	v_mfma_f32_16x16x32_bf16 v[132:135], v[170:173], v[186:189], v[132:135]
	v_mfma_f32_16x16x32_bf16 v[128:131], v[178:181], v[186:189], v[128:131]
	v_mfma_f32_16x16x32_bf16 v[116:119], v[170:173], v[204:207], v[116:119]
	v_mfma_f32_16x16x32_bf16 v[112:115], v[178:181], v[204:207], v[112:115]
	v_mfma_f32_16x16x32_bf16 v[100:103], v[170:173], v[212:215], v[100:103]
	v_mfma_f32_16x16x32_bf16 v[96:99], v[178:181], v[212:215], v[96:99]
	v_mfma_f32_16x16x32_bf16 v[84:87], v[170:173], v[238:241], v[84:87]
	v_mfma_f32_16x16x32_bf16 v[80:83], v[178:181], v[238:241], v[80:83]
	v_mfma_f32_16x16x32_bf16 v[132:135], v[174:177], v[200:203], v[132:135]
	v_mfma_f32_16x16x32_bf16 v[128:131], v[182:185], v[200:203], v[128:131]
	v_mfma_f32_16x16x32_bf16 v[116:119], v[174:177], v[208:211], v[116:119]
	v_mfma_f32_16x16x32_bf16 v[112:115], v[182:185], v[208:211], v[112:115]
	v_mfma_f32_16x16x32_bf16 v[100:103], v[174:177], v[234:237], v[100:103]
	v_mfma_f32_16x16x32_bf16 v[96:99], v[182:185], v[234:237], v[96:99]
	v_mfma_f32_16x16x32_bf16 v[84:87], v[174:177], v[242:245], v[84:87]
	v_mfma_f32_16x16x32_bf16 v[80:83], v[182:185], v[242:245], v[80:83]
	s_setprio 0
	s_barrier
	s_add_i32 s61, s61, s41
	v_lshl_add_u64 v[160:161], s[10:11], 0, v[148:149]
	s_mov_b32 m0, s61
	ds_read_b128 v[186:189], v168 offset:16384
	ds_read_b128 v[200:203], v168 offset:17408
	ds_read_b128 v[204:207], v168 offset:18432
	ds_read_b128 v[208:211], v168 offset:19456
	ds_read_b128 v[212:215], v168 offset:20480
	ds_read_b128 v[234:237], v168 offset:21504
	ds_read_b128 v[238:241], v168 offset:22528
	ds_read_b128 v[242:245], v168 offset:23552
	global_load_lds_dwordx4 v[160:161], off
	s_add_i32 m0, s61, 0x2000
	s_add_u32 s62, s10, 0x40000
	v_lshl_add_u64 v[190:191], s[10:11], 0, v[144:145]
	s_addc_u32 s63, s11, 0
	s_add_i32 s61, s64, s41
	global_load_lds_dwordx4 v[190:191], off
	v_lshl_add_u64 v[218:219], s[62:63], 0, v[148:149]
	s_mov_b32 m0, s61
	v_lshl_add_u64 v[220:221], s[12:13], 0, v[146:147]
	global_load_lds_dwordx4 v[218:219], off
	s_add_i32 m0, s61, 0x2000
	v_lshl_add_u64 v[218:219], s[62:63], 0, v[144:145]
	global_load_lds_dwordx4 v[218:219], off
	s_mov_b32 m0, s48
	v_lshl_add_u64 v[218:219], s[12:13], 0, v[150:151]
	global_load_lds_dwordx4 v[218:219], off
	s_mov_b32 m0, s49
	s_nop 0
	global_load_lds_dwordx4 v[220:221], off
	s_waitcnt vmcnt(8)
	s_waitcnt lgkmcnt(0)
	s_barrier
; #define PG8_STAGE(bufoff, gbase, voff) do { _Pragma("unroll") for (int _i = 0; _i < 2; ++_i) \
;         __builtin_amdgcn_global_load_lds((const unsigned*)((const char*)(gbase) + (voff)[_i]), (PG8_LAS unsigned*)(lds + (bufoff) + ldsw + _i * 8192), 16, 0, 0); } while (0)
; #define PG8_LDA(dst, b, h) do { _Pragma("unroll") for (int m = 0; m < 4; ++m) _Pragma("unroll") for (int k = 0; k < 2; ++k) dst[m][k] = *(const PG8_LAS bf16x8*)(lds + PG8_SA(b, h) + aoff + m * 2048 + k * 1024); } while (0)
; #define PG8_LDB(dst, b, h) do { _Pragma("unroll") for (int n = 0; n < 2; ++n) _Pragma("unroll") for (int k = 0; k < 2; ++k) dst[n][k] = *(const PG8_LAS bf16x8*)(lds + PG8_SB(b, h) + boff + n * 2048 + k * 1024); } while (0)
; #define PG8_MMA(ai, bj, At, Bt) do { __builtin_amdgcn_s_setprio(1); _Pragma("unroll") for (int m = 0; m < 4; ++m) _Pragma("unroll") for (int n = 0; n < 2; ++n) _Pragma("unroll") for (int k = 0; k < 2; ++k) \
;         acc[ai][bj][m][n] = __builtin_amdgcn_mfma_f32_16x16x32_bf16(Bt[n][k], At[m][k], acc[ai][bj][m][n], 0, 0, 0); __builtin_amdgcn_s_setprio(0); } while (0)
; #define PG8_WAIT_V(n) asm volatile("s_waitcnt vmcnt(" #n ")" ::: "memory")
; #define PG8_WAIT_L(n) asm volatile("s_waitcnt lgkmcnt(" #n ")" ::: "memory")
; #define PG8_BAR __builtin_amdgcn_s_barrier()
; #define PG8_SCHED __builtin_amdgcn_sched_barrier(0)
; template <class Epi, class Sched, bool ALIGN_EPI = false, bool SP2 = false>
; __device__ __forceinline__ void gemm_phase(PG8_LAS unsigned char* lds, const Gemm g, const Sched& S, const Epi& E, const int tid_in) {
;     ...
;             PG8_WAIT_V(8); PG8_WAIT_L(0); PG8_BAR; PG8_MMA(1, 0, At, B0); PG8_MMA(1, 1, At, B1); PG8_BAR; PG8_SCHED;
;             PG8_LDB(B0, 1, 0); PG8_LDB(B1, 1, 1); PG8_SCHED; PG8_LDA(At, 1, 0); PG8_STAGE(PG8_SA(0, 1), a2 + hstep, voffA);
;             PG8_WAIT_V(8); PG8_WAIT_L(0); PG8_BAR; PG8_MMA(0, 0, At, B0); PG8_MMA(0, 1, At, B1); PG8_BAR; PG8_SCHED;
	s_setprio 1
	v_mfma_f32_16x16x32_bf16 v[72:75], v[56:59], v[186:189], v[72:75]
	v_mfma_f32_16x16x32_bf16 v[60:63], v[68:71], v[186:189], v[60:63]
	v_mfma_f32_16x16x32_bf16 v[44:47], v[56:59], v[204:207], v[44:47]
	v_mfma_f32_16x16x32_bf16 v[40:43], v[68:71], v[204:207], v[40:43]
	v_mfma_f32_16x16x32_bf16 v[28:31], v[56:59], v[212:215], v[28:31]
	v_mfma_f32_16x16x32_bf16 v[24:27], v[68:71], v[212:215], v[24:27]
	v_mfma_f32_16x16x32_bf16 v[12:15], v[56:59], v[238:241], v[12:15]
	v_mfma_f32_16x16x32_bf16 v[8:11], v[68:71], v[238:241], v[8:11]
	v_mfma_f32_16x16x32_bf16 v[72:75], v[64:67], v[200:203], v[72:75]
	v_mfma_f32_16x16x32_bf16 v[60:63], v[76:79], v[200:203], v[60:63]
	v_mfma_f32_16x16x32_bf16 v[44:47], v[64:67], v[208:211], v[44:47]
	v_mfma_f32_16x16x32_bf16 v[40:43], v[76:79], v[208:211], v[40:43]
	v_mfma_f32_16x16x32_bf16 v[28:31], v[64:67], v[234:237], v[28:31]
	v_mfma_f32_16x16x32_bf16 v[24:27], v[76:79], v[234:237], v[24:27]
	v_mfma_f32_16x16x32_bf16 v[12:15], v[64:67], v[242:245], v[12:15]
	v_mfma_f32_16x16x32_bf16 v[8:11], v[76:79], v[242:245], v[8:11]
	v_mfma_f32_16x16x32_bf16 v[52:55], v[170:173], v[186:189], v[52:55]
	v_mfma_f32_16x16x32_bf16 v[48:51], v[178:181], v[186:189], v[48:51]
	v_mfma_f32_16x16x32_bf16 v[36:39], v[170:173], v[204:207], v[36:39]
	v_mfma_f32_16x16x32_bf16 v[32:35], v[178:181], v[204:207], v[32:35]
	v_mfma_f32_16x16x32_bf16 v[20:23], v[170:173], v[212:215], v[20:23]
	v_mfma_f32_16x16x32_bf16 v[16:19], v[178:181], v[212:215], v[16:19]
	v_mfma_f32_16x16x32_bf16 v[4:7], v[170:173], v[238:241], v[4:7]
	v_mfma_f32_16x16x32_bf16 v[0:3], v[178:181], v[238:241], v[0:3]
	v_mfma_f32_16x16x32_bf16 v[52:55], v[174:177], v[200:203], v[52:55]
	v_mfma_f32_16x16x32_bf16 v[48:51], v[182:185], v[200:203], v[48:51]
	v_mfma_f32_16x16x32_bf16 v[36:39], v[174:177], v[208:211], v[36:39]
	v_mfma_f32_16x16x32_bf16 v[32:35], v[182:185], v[208:211], v[32:35]
	v_mfma_f32_16x16x32_bf16 v[20:23], v[174:177], v[234:237], v[20:23]
	v_mfma_f32_16x16x32_bf16 v[16:19], v[182:185], v[234:237], v[16:19]
	v_mfma_f32_16x16x32_bf16 v[4:7], v[174:177], v[242:245], v[4:7]
	v_mfma_f32_16x16x32_bf16 v[0:3], v[182:185], v[242:245], v[0:3]
	s_setprio 0
	s_barrier
	s_add_i32 s61, 0, 0x18000
	s_add_i32 s62, 0, 0x1c000
	v_add_u32_e32 v76, s61, v162
	v_add_u32_e32 v169, s62, v162
	ds_read_b128 v[56:59], v76
	ds_read_b128 v[64:67], v76 offset:1024
	ds_read_b128 v[68:71], v76 offset:2048
	ds_read_b128 v[76:79], v76 offset:3072
	ds_read_b128 v[170:173], v169
	ds_read_b128 v[174:177], v169 offset:1024
	ds_read_b128 v[178:181], v169 offset:2048
	ds_read_b128 v[182:185], v169 offset:3072
	s_add_u32 s12, s12, 0x40000
	s_addc_u32 s13, s13, 0
	s_mov_b32 m0, s50
	v_lshl_add_u64 v[230:231], s[12:13], 0, v[150:151]
	ds_read_b128 v[186:189], v168 offset:32768
	ds_read_b128 v[200:203], v168 offset:33792
	ds_read_b128 v[204:207], v168 offset:34816
	ds_read_b128 v[208:211], v168 offset:35840
	ds_read_b128 v[212:215], v168 offset:36864
	ds_read_b128 v[234:237], v168 offset:37888
	ds_read_b128 v[238:241], v168 offset:38912
	ds_read_b128 v[242:245], v168 offset:39936
	global_load_lds_dwordx4 v[230:231], off
	s_mov_b32 m0, s51
	v_lshl_add_u64 v[230:231], s[12:13], 0, v[146:147]
	global_load_lds_dwordx4 v[230:231], off
	s_waitcnt vmcnt(8)
	s_waitcnt lgkmcnt(0)
	s_barrier
	s_setprio 1
	v_mfma_f32_16x16x32_bf16 v[140:143], v[56:59], v[186:189], v[140:143]
	v_mfma_f32_16x16x32_bf16 v[136:139], v[68:71], v[186:189], v[136:139]
	v_mfma_f32_16x16x32_bf16 v[124:127], v[56:59], v[204:207], v[124:127]
	v_mfma_f32_16x16x32_bf16 v[120:123], v[68:71], v[204:207], v[120:123]
	v_mfma_f32_16x16x32_bf16 v[108:111], v[56:59], v[212:215], v[108:111]
	v_mfma_f32_16x16x32_bf16 v[104:107], v[68:71], v[212:215], v[104:107]
	v_mfma_f32_16x16x32_bf16 v[92:95], v[56:59], v[238:241], v[92:95]
	v_mfma_f32_16x16x32_bf16 v[88:91], v[68:71], v[238:241], v[88:91]
	v_mfma_f32_16x16x32_bf16 v[140:143], v[64:67], v[200:203], v[140:143]
	v_mfma_f32_16x16x32_bf16 v[136:139], v[76:79], v[200:203], v[136:139]
	v_mfma_f32_16x16x32_bf16 v[124:127], v[64:67], v[208:211], v[124:127]
	v_mfma_f32_16x16x32_bf16 v[120:123], v[76:79], v[208:211], v[120:123]
	v_mfma_f32_16x16x32_bf16 v[108:111], v[64:67], v[234:237], v[108:111]
	v_mfma_f32_16x16x32_bf16 v[104:107], v[76:79], v[234:237], v[104:107]
	v_mfma_f32_16x16x32_bf16 v[92:95], v[64:67], v[242:245], v[92:95]
	v_mfma_f32_16x16x32_bf16 v[88:91], v[76:79], v[242:245], v[88:91]
	v_mfma_f32_16x16x32_bf16 v[132:135], v[170:173], v[186:189], v[132:135]
	v_mfma_f32_16x16x32_bf16 v[128:131], v[178:181], v[186:189], v[128:131]
	v_mfma_f32_16x16x32_bf16 v[116:119], v[170:173], v[204:207], v[116:119]
	v_mfma_f32_16x16x32_bf16 v[112:115], v[178:181], v[204:207], v[112:115]
	v_mfma_f32_16x16x32_bf16 v[100:103], v[170:173], v[212:215], v[100:103]
	v_mfma_f32_16x16x32_bf16 v[96:99], v[178:181], v[212:215], v[96:99]
	v_mfma_f32_16x16x32_bf16 v[84:87], v[170:173], v[238:241], v[84:87]
	v_mfma_f32_16x16x32_bf16 v[80:83], v[178:181], v[238:241], v[80:83]
	v_mfma_f32_16x16x32_bf16 v[132:135], v[174:177], v[200:203], v[132:135]
	v_mfma_f32_16x16x32_bf16 v[128:131], v[182:185], v[200:203], v[128:131]
	v_mfma_f32_16x16x32_bf16 v[116:119], v[174:177], v[208:211], v[116:119]
	v_mfma_f32_16x16x32_bf16 v[112:115], v[182:185], v[208:211], v[112:115]
	v_mfma_f32_16x16x32_bf16 v[100:103], v[174:177], v[234:237], v[100:103]
	v_mfma_f32_16x16x32_bf16 v[96:99], v[182:185], v[234:237], v[96:99]
	v_mfma_f32_16x16x32_bf16 v[84:87], v[174:177], v[242:245], v[84:87]
	v_mfma_f32_16x16x32_bf16 v[80:83], v[182:185], v[242:245], v[80:83]
	s_setprio 0
	s_barrier
; #define PG8_STAGE(bufoff, gbase, voff) do { _Pragma("unroll") for (int _i = 0; _i < 2; ++_i) \
;         __builtin_amdgcn_global_load_lds((const unsigned*)((const char*)(gbase) + (voff)[_i]), (PG8_LAS unsigned*)(lds + (bufoff) + ldsw + _i * 8192), 16, 0, 0); } while (0)
; #define PG8_LDA(dst, b, h) do { _Pragma("unroll") for (int m = 0; m < 4; ++m) _Pragma("unroll") for (int k = 0; k < 2; ++k) dst[m][k] = *(const PG8_LAS bf16x8*)(lds + PG8_SA(b, h) + aoff + m * 2048 + k * 1024); } while (0)
; #define PG8_MMA(ai, bj, At, Bt) do { __builtin_amdgcn_s_setprio(1); _Pragma("unroll") for (int m = 0; m < 4; ++m) _Pragma("unroll") for (int n = 0; n < 2; ++n) _Pragma("unroll") for (int k = 0; k < 2; ++k) \
;         acc[ai][bj][m][n] = __builtin_amdgcn_mfma_f32_16x16x32_bf16(Bt[n][k], At[m][k], acc[ai][bj][m][n], 0, 0, 0); __builtin_amdgcn_s_setprio(0); } while (0)
; #define PG8_WAIT_V(n) asm volatile("s_waitcnt vmcnt(" #n ")" ::: "memory")
; #define PG8_WAIT_L(n) asm volatile("s_waitcnt lgkmcnt(" #n ")" ::: "memory")
; #define PG8_BAR __builtin_amdgcn_s_barrier()
; #define PG8_SCHED __builtin_amdgcn_sched_barrier(0)
; template <class Epi, class Sched, bool ALIGN_EPI = false, bool SP2 = false>
; __device__ __forceinline__ void gemm_phase(PG8_LAS unsigned char* lds, const Gemm g, const Sched& S, const Epi& E, const int tid_in) {
;     ...
;             PG8_LDA(At, 1, 1); PG8_STAGE(PG8_SB(1, 0), b3, voffB); PG8_STAGE(PG8_SB(1, 1), b3 + hstep, voffB); PG8_STAGE(PG8_SA(1, 0), a3, voffA);
;             PG8_WAIT_V(8); PG8_WAIT_L(0); PG8_BAR; PG8_MMA(1, 0, At, B0); PG8_MMA(1, 1, At, B1); PG8_BAR; PG8_SCHED;
;     ...
;         if constexpr (ALIGN_EPI) { if (wr == 0) PG8_BAR; }
	s_add_i32 s12, s61, s41
	v_lshl_add_u64 v[160:161], v[160:161], 0, s[92:93]
	s_mov_b32 m0, s12
	ds_read_b128 v[186:189], v168 offset:49152
	ds_read_b128 v[200:203], v168 offset:50176
	ds_read_b128 v[204:207], v168 offset:51200
	ds_read_b128 v[208:211], v168 offset:52224
	ds_read_b128 v[212:215], v168 offset:53248
	ds_read_b128 v[234:237], v168 offset:54272
	ds_read_b128 v[238:241], v168 offset:55296
	ds_read_b128 v[242:245], v168 offset:56320
	global_load_lds_dwordx4 v[160:161], off
	s_add_i32 m0, s12, 0x2000
	s_add_u32 s10, s10, 0x40080
	v_lshl_add_u64 v[160:161], v[190:191], 0, s[92:93]
	s_addc_u32 s11, s11, 0
	s_add_i32 s12, s62, s41
	global_load_lds_dwordx4 v[160:161], off
	s_mov_b32 m0, s12
	v_lshl_add_u64 v[160:161], s[10:11], 0, v[148:149]
	global_load_lds_dwordx4 v[160:161], off
	s_add_i32 m0, s12, 0x2000
	v_lshl_add_u64 v[160:161], s[10:11], 0, v[144:145]
	global_load_lds_dwordx4 v[160:161], off
	s_mov_b32 m0, s54
	v_lshl_add_u64 v[160:161], v[218:219], 0, s[92:93]
	global_load_lds_dwordx4 v[160:161], off
	s_mov_b32 m0, s55
	v_lshl_add_u64 v[160:161], v[220:221], 0, s[92:93]
	global_load_lds_dwordx4 v[160:161], off
	s_waitcnt vmcnt(8)
	s_waitcnt lgkmcnt(0)
	s_barrier
	s_setprio 1
	v_mfma_f32_16x16x32_bf16 v[72:75], v[56:59], v[186:189], v[72:75]
	v_mfma_f32_16x16x32_bf16 v[60:63], v[68:71], v[186:189], v[60:63]
	v_mfma_f32_16x16x32_bf16 v[44:47], v[56:59], v[204:207], v[44:47]
	v_mfma_f32_16x16x32_bf16 v[40:43], v[68:71], v[204:207], v[40:43]
	v_mfma_f32_16x16x32_bf16 v[28:31], v[56:59], v[212:215], v[28:31]
	v_mfma_f32_16x16x32_bf16 v[24:27], v[68:71], v[212:215], v[24:27]
	v_mfma_f32_16x16x32_bf16 v[12:15], v[56:59], v[238:241], v[12:15]
	v_mfma_f32_16x16x32_bf16 v[8:11], v[68:71], v[238:241], v[8:11]
	v_mfma_f32_16x16x32_bf16 v[72:75], v[64:67], v[200:203], v[72:75]
	v_mfma_f32_16x16x32_bf16 v[60:63], v[76:79], v[200:203], v[60:63]
	v_mfma_f32_16x16x32_bf16 v[44:47], v[64:67], v[208:211], v[44:47]
	v_mfma_f32_16x16x32_bf16 v[40:43], v[76:79], v[208:211], v[40:43]
	v_mfma_f32_16x16x32_bf16 v[28:31], v[64:67], v[234:237], v[28:31]
	v_mfma_f32_16x16x32_bf16 v[24:27], v[76:79], v[234:237], v[24:27]
	v_mfma_f32_16x16x32_bf16 v[12:15], v[64:67], v[242:245], v[12:15]
	v_mfma_f32_16x16x32_bf16 v[8:11], v[76:79], v[242:245], v[8:11]
	v_mfma_f32_16x16x32_bf16 v[52:55], v[170:173], v[186:189], v[52:55]
	v_mfma_f32_16x16x32_bf16 v[48:51], v[178:181], v[186:189], v[48:51]
	v_mfma_f32_16x16x32_bf16 v[36:39], v[170:173], v[204:207], v[36:39]
	v_mfma_f32_16x16x32_bf16 v[32:35], v[178:181], v[204:207], v[32:35]
	v_mfma_f32_16x16x32_bf16 v[20:23], v[170:173], v[212:215], v[20:23]
	v_mfma_f32_16x16x32_bf16 v[16:19], v[178:181], v[212:215], v[16:19]
	v_mfma_f32_16x16x32_bf16 v[4:7], v[170:173], v[238:241], v[4:7]
	v_mfma_f32_16x16x32_bf16 v[0:3], v[178:181], v[238:241], v[0:3]
	v_mfma_f32_16x16x32_bf16 v[52:55], v[174:177], v[200:203], v[52:55]
	v_mfma_f32_16x16x32_bf16 v[48:51], v[182:185], v[200:203], v[48:51]
	v_mfma_f32_16x16x32_bf16 v[36:39], v[174:177], v[208:211], v[36:39]
	v_mfma_f32_16x16x32_bf16 v[32:35], v[182:185], v[208:211], v[32:35]
	v_mfma_f32_16x16x32_bf16 v[20:23], v[174:177], v[234:237], v[20:23]
	v_mfma_f32_16x16x32_bf16 v[16:19], v[182:185], v[234:237], v[16:19]
	v_mfma_f32_16x16x32_bf16 v[4:7], v[174:177], v[242:245], v[4:7]
	v_mfma_f32_16x16x32_bf16 v[0:3], v[182:185], v[242:245], v[0:3]
	s_setprio 0
	s_barrier
	s_add_i32 s60, s60, 2
	s_add_u32 s4, s4, 0x100
	s_addc_u32 s5, s5, 0
	s_add_u32 s58, s58, 0x100
	s_addc_u32 s59, s59, 0
	s_cmp_gt_u32 s60, 13
	s_cbranch_scc0 .LBB0_42
	s_and_b64 vcc, exec, s[34:35]
	s_cbranch_vccz .LBB0_45
	s_barrier

; #define PG8_STAGE(bufoff, gbase, voff) do { _Pragma("unroll") for (int _i = 0; _i < 2; ++_i) \
;         __builtin_amdgcn_global_load_lds((const unsigned*)((const char*)(gbase) + (voff)[_i]), (PG8_LAS unsigned*)(lds + (bufoff) + ldsw + _i * 8192), 16, 0, 0); } while (0)
; #define PG8_LDA(dst, b, h) do { _Pragma("unroll") for (int m = 0; m < 4; ++m) _Pragma("unroll") for (int k = 0; k < 2; ++k) dst[m][k] = *(const PG8_LAS bf16x8*)(lds + PG8_SA(b, h) + aoff + m * 2048 + k * 1024); } while (0)
; #define PG8_LDB(dst, b, h) do { _Pragma("unroll") for (int n = 0; n < 2; ++n) _Pragma("unroll") for (int k = 0; k < 2; ++k) dst[n][k] = *(const PG8_LAS bf16x8*)(lds + PG8_SB(b, h) + boff + n * 2048 + k * 1024); } while (0)
; #define PG8_MMA(ai, bj, At, Bt) do { __builtin_amdgcn_s_setprio(1); _Pragma("unroll") for (int m = 0; m < 4; ++m) _Pragma("unroll") for (int n = 0; n < 2; ++n) _Pragma("unroll") for (int k = 0; k < 2; ++k) \
;         acc[ai][bj][m][n] = __builtin_amdgcn_mfma_f32_16x16x32_bf16(Bt[n][k], At[m][k], acc[ai][bj][m][n], 0, 0, 0); __builtin_amdgcn_s_setprio(0); } while (0)
; #define PG8_WAIT_V(n) asm volatile("s_waitcnt vmcnt(" #n ")" ::: "memory")
; #define PG8_WAIT_L(n) asm volatile("s_waitcnt lgkmcnt(" #n ")" ::: "memory")
; #define PG8_BAR __builtin_amdgcn_s_barrier()
; #define PG8_SCHED __builtin_amdgcn_sched_barrier(0)
; template <class Epi, class Sched, bool ALIGN_EPI = false, bool SP2 = false>
; __device__ __forceinline__ void gemm_phase(PG8_LAS unsigned char* lds, const Gemm g, const Sched& S, const Epi& E, const int tid_in) {
;     ...
;             PG8_LDB(B0, 0, 0); PG8_LDB(B1, 0, 1); PG8_SCHED; PG8_LDA(At, 0, 0); PG8_STAGE(PG8_SA(1, 1), a1 + hstep, voffA);
;             PG8_WAIT_V(8); PG8_WAIT_L(0); PG8_BAR; PG8_MMA(0, 0, At, B0); PG8_MMA(0, 1, At, B1); PG8_BAR; PG8_SCHED;
;             PG8_LDA(At, 0, 1); PG8_STAGE(PG8_SB(0, 0), b2, voffB); PG8_STAGE(PG8_SB(0, 1), b2 + hstep, voffB); PG8_STAGE(PG8_SA(0, 0), a2, voffA);
;             PG8_WAIT_V(8); PG8_WAIT_L(0); PG8_BAR; PG8_MMA(1, 0, At, B0); PG8_MMA(1, 1, At, B1); PG8_BAR; PG8_SCHED;
.LBB0_284:
	s_add_i32 s52, s26, 2
	s_add_u32 s53, s24, 0x80
	s_addc_u32 s27, s25, 0
	s_add_i32 s56, 0, 0x10000
	s_cmp_eq_u32 s28, s26
	s_cselect_b32 s27, s21, s27
	s_cselect_b32 s26, s20, s53
	s_cselect_b32 s55, s23, s51
	s_cselect_b32 s54, s22, s29
	s_add_i32 s53, 0, 0x14000
	v_add_u32_e32 v154, s56, v143
	v_add_u32_e32 v170, s53, v143
	ds_read_b128 v[138:141], v154
	ds_read_b128 v[146:149], v154 offset:1024
	ds_read_b128 v[150:153], v154 offset:2048
	ds_read_b128 v[154:157], v154 offset:3072
	ds_read_b128 v[158:161], v170
	ds_read_b128 v[162:165], v170 offset:1024
	ds_read_b128 v[166:169], v170 offset:2048
	ds_read_b128 v[170:173], v170 offset:3072
	v_lshl_add_u64 v[190:191], s[24:25], 0, v[134:135]
	s_add_i32 m0, s38, 0xc000
	ds_read_b128 v[174:177], v145
	ds_read_b128 v[178:181], v145 offset:1024
	ds_read_b128 v[182:185], v145 offset:2048
	ds_read_b128 v[186:189], v145 offset:3072
	ds_read_b128 v[200:203], v145 offset:4096
	ds_read_b128 v[204:207], v145 offset:5120
	ds_read_b128 v[208:211], v145 offset:6144
	ds_read_b128 v[212:215], v145 offset:7168
	global_load_lds_dwordx4 v[190:191], off
	s_add_i32 m0, s38, 0xe000
	v_lshl_add_u64 v[190:191], s[24:25], 0, v[136:137]
	global_load_lds_dwordx4 v[190:191], off
	s_waitcnt vmcnt(8)
	s_waitcnt lgkmcnt(0)
	s_barrier
	s_setprio 1
	v_mfma_f32_16x16x32_bf16 v[124:127], v[138:141], v[174:177], v[124:127]
	v_mfma_f32_16x16x32_bf16 v[120:123], v[150:153], v[174:177], v[120:123]
	v_mfma_f32_16x16x32_bf16 v[108:111], v[138:141], v[182:185], v[108:111]
	v_mfma_f32_16x16x32_bf16 v[104:107], v[150:153], v[182:185], v[104:107]
	v_mfma_f32_16x16x32_bf16 v[92:95], v[138:141], v[200:203], v[92:95]
	v_mfma_f32_16x16x32_bf16 v[88:91], v[150:153], v[200:203], v[88:91]
	v_mfma_f32_16x16x32_bf16 v[76:79], v[138:141], v[208:211], v[76:79]
	v_mfma_f32_16x16x32_bf16 v[72:75], v[150:153], v[208:211], v[72:75]
	v_mfma_f32_16x16x32_bf16 v[124:127], v[146:149], v[178:181], v[124:127]
	v_mfma_f32_16x16x32_bf16 v[120:123], v[154:157], v[178:181], v[120:123]
	v_mfma_f32_16x16x32_bf16 v[108:111], v[146:149], v[186:189], v[108:111]
	v_mfma_f32_16x16x32_bf16 v[104:107], v[154:157], v[186:189], v[104:107]
	v_mfma_f32_16x16x32_bf16 v[92:95], v[146:149], v[204:207], v[92:95]
	v_mfma_f32_16x16x32_bf16 v[88:91], v[154:157], v[204:207], v[88:91]
	v_mfma_f32_16x16x32_bf16 v[76:79], v[146:149], v[212:215], v[76:79]
	v_mfma_f32_16x16x32_bf16 v[72:75], v[154:157], v[212:215], v[72:75]
	v_mfma_f32_16x16x32_bf16 v[116:119], v[158:161], v[174:177], v[116:119]
	v_mfma_f32_16x16x32_bf16 v[112:115], v[166:169], v[174:177], v[112:115]
	v_mfma_f32_16x16x32_bf16 v[100:103], v[158:161], v[182:185], v[100:103]
	v_mfma_f32_16x16x32_bf16 v[96:99], v[166:169], v[182:185], v[96:99]
	v_mfma_f32_16x16x32_bf16 v[84:87], v[158:161], v[200:203], v[84:87]
	v_mfma_f32_16x16x32_bf16 v[80:83], v[166:169], v[200:203], v[80:83]
	v_mfma_f32_16x16x32_bf16 v[68:71], v[158:161], v[208:211], v[68:71]
	v_mfma_f32_16x16x32_bf16 v[64:67], v[166:169], v[208:211], v[64:67]
	v_mfma_f32_16x16x32_bf16 v[116:119], v[162:165], v[178:181], v[116:119]
	v_mfma_f32_16x16x32_bf16 v[112:115], v[170:173], v[178:181], v[112:115]
	v_mfma_f32_16x16x32_bf16 v[100:103], v[162:165], v[186:189], v[100:103]
	v_mfma_f32_16x16x32_bf16 v[96:99], v[170:173], v[186:189], v[96:99]
	v_mfma_f32_16x16x32_bf16 v[84:87], v[162:165], v[204:207], v[84:87]
	v_mfma_f32_16x16x32_bf16 v[80:83], v[170:173], v[204:207], v[80:83]
	v_mfma_f32_16x16x32_bf16 v[68:71], v[162:165], v[212:215], v[68:71]
	v_mfma_f32_16x16x32_bf16 v[64:67], v[170:173], v[212:215], v[64:67]
	s_setprio 0
	s_barrier
	s_add_i32 s56, s56, s35
	v_lshl_add_u64 v[190:191], s[54:55], 0, v[192:193]
	s_mov_b32 m0, s56
	ds_read_b128 v[174:177], v145 offset:16384
	ds_read_b128 v[178:181], v145 offset:17408
	ds_read_b128 v[182:185], v145 offset:18432
	ds_read_b128 v[186:189], v145 offset:19456
	ds_read_b128 v[200:203], v145 offset:20480
	ds_read_b128 v[204:207], v145 offset:21504
	ds_read_b128 v[208:211], v145 offset:22528
	ds_read_b128 v[212:215], v145 offset:23552
	global_load_lds_dwordx4 v[190:191], off
	s_add_i32 m0, s56, 0x2000
	v_lshl_add_u64 v[218:219], s[54:55], 0, v[132:133]
	s_add_u32 s54, s54, s12
	s_addc_u32 s55, s55, 0
	s_add_i32 s53, s53, s35
	global_load_lds_dwordx4 v[218:219], off
	v_lshl_add_u64 v[220:221], s[54:55], 0, v[192:193]
	s_mov_b32 m0, s53
	v_lshl_add_u64 v[230:231], s[54:55], 0, v[132:133]
	global_load_lds_dwordx4 v[220:221], off
	s_add_i32 m0, s53, 0x2000
	v_lshl_add_u64 v[232:233], s[26:27], 0, v[128:129]
	global_load_lds_dwordx4 v[230:231], off
	s_mov_b32 m0, s38
	v_lshl_add_u64 v[234:235], s[26:27], 0, v[130:131]
	global_load_lds_dwordx4 v[232:233], off
	s_mov_b32 m0, s39
	s_nop 0
	global_load_lds_dwordx4 v[234:235], off
	s_waitcnt vmcnt(8)
	s_waitcnt lgkmcnt(0)
	s_barrier
; #define PG8_STAGE(bufoff, gbase, voff) do { _Pragma("unroll") for (int _i = 0; _i < 2; ++_i) \
;         __builtin_amdgcn_global_load_lds((const unsigned*)((const char*)(gbase) + (voff)[_i]), (PG8_LAS unsigned*)(lds + (bufoff) + ldsw + _i * 8192), 16, 0, 0); } while (0)
; #define PG8_LDA(dst, b, h) do { _Pragma("unroll") for (int m = 0; m < 4; ++m) _Pragma("unroll") for (int k = 0; k < 2; ++k) dst[m][k] = *(const PG8_LAS bf16x8*)(lds + PG8_SA(b, h) + aoff + m * 2048 + k * 1024); } while (0)
; #define PG8_LDB(dst, b, h) do { _Pragma("unroll") for (int n = 0; n < 2; ++n) _Pragma("unroll") for (int k = 0; k < 2; ++k) dst[n][k] = *(const PG8_LAS bf16x8*)(lds + PG8_SB(b, h) + boff + n * 2048 + k * 1024); } while (0)
; #define PG8_MMA(ai, bj, At, Bt) do { __builtin_amdgcn_s_setprio(1); _Pragma("unroll") for (int m = 0; m < 4; ++m) _Pragma("unroll") for (int n = 0; n < 2; ++n) _Pragma("unroll") for (int k = 0; k < 2; ++k) \
;         acc[ai][bj][m][n] = __builtin_amdgcn_mfma_f32_16x16x32_bf16(Bt[n][k], At[m][k], acc[ai][bj][m][n], 0, 0, 0); __builtin_amdgcn_s_setprio(0); } while (0)
; #define PG8_WAIT_V(n) asm volatile("s_waitcnt vmcnt(" #n ")" ::: "memory")
; #define PG8_WAIT_L(n) asm volatile("s_waitcnt lgkmcnt(" #n ")" ::: "memory")
; #define PG8_BAR __builtin_amdgcn_s_barrier()
; #define PG8_SCHED __builtin_amdgcn_sched_barrier(0)
; template <class Epi, class Sched, bool ALIGN_EPI = false, bool SP2 = false>
; __device__ __forceinline__ void gemm_phase(PG8_LAS unsigned char* lds, const Gemm g, const Sched& S, const Epi& E, const int tid_in) {
;     ...
;             PG8_WAIT_V(8); PG8_WAIT_L(0); PG8_BAR; PG8_MMA(1, 0, At, B0); PG8_MMA(1, 1, At, B1); PG8_BAR; PG8_SCHED;
;             PG8_LDB(B0, 1, 0); PG8_LDB(B1, 1, 1); PG8_SCHED; PG8_LDA(At, 1, 0); PG8_STAGE(PG8_SA(0, 1), a2 + hstep, voffA);
;             PG8_WAIT_V(8); PG8_WAIT_L(0); PG8_BAR; PG8_MMA(0, 0, At, B0); PG8_MMA(0, 1, At, B1); PG8_BAR; PG8_SCHED;
	s_setprio 1
	v_mfma_f32_16x16x32_bf16 v[60:63], v[138:141], v[174:177], v[60:63]
	v_mfma_f32_16x16x32_bf16 v[56:59], v[150:153], v[174:177], v[56:59]
	v_mfma_f32_16x16x32_bf16 v[44:47], v[138:141], v[182:185], v[44:47]
	v_mfma_f32_16x16x32_bf16 v[40:43], v[150:153], v[182:185], v[40:43]
	v_mfma_f32_16x16x32_bf16 v[28:31], v[138:141], v[200:203], v[28:31]
	v_mfma_f32_16x16x32_bf16 v[24:27], v[150:153], v[200:203], v[24:27]
	v_mfma_f32_16x16x32_bf16 v[12:15], v[138:141], v[208:211], v[12:15]
	v_mfma_f32_16x16x32_bf16 v[8:11], v[150:153], v[208:211], v[8:11]
	v_mfma_f32_16x16x32_bf16 v[60:63], v[146:149], v[178:181], v[60:63]
	v_mfma_f32_16x16x32_bf16 v[56:59], v[154:157], v[178:181], v[56:59]
	v_mfma_f32_16x16x32_bf16 v[44:47], v[146:149], v[186:189], v[44:47]
	v_mfma_f32_16x16x32_bf16 v[40:43], v[154:157], v[186:189], v[40:43]
	v_mfma_f32_16x16x32_bf16 v[28:31], v[146:149], v[204:207], v[28:31]
	v_mfma_f32_16x16x32_bf16 v[24:27], v[154:157], v[204:207], v[24:27]
	v_mfma_f32_16x16x32_bf16 v[12:15], v[146:149], v[212:215], v[12:15]
	v_mfma_f32_16x16x32_bf16 v[8:11], v[154:157], v[212:215], v[8:11]
	v_mfma_f32_16x16x32_bf16 v[52:55], v[158:161], v[174:177], v[52:55]
	v_mfma_f32_16x16x32_bf16 v[48:51], v[166:169], v[174:177], v[48:51]
	v_mfma_f32_16x16x32_bf16 v[36:39], v[158:161], v[182:185], v[36:39]
	v_mfma_f32_16x16x32_bf16 v[32:35], v[166:169], v[182:185], v[32:35]
	v_mfma_f32_16x16x32_bf16 v[20:23], v[158:161], v[200:203], v[20:23]
	v_mfma_f32_16x16x32_bf16 v[16:19], v[166:169], v[200:203], v[16:19]
	v_mfma_f32_16x16x32_bf16 v[4:7], v[158:161], v[208:211], v[4:7]
	v_mfma_f32_16x16x32_bf16 v[0:3], v[166:169], v[208:211], v[0:3]
	v_mfma_f32_16x16x32_bf16 v[52:55], v[162:165], v[178:181], v[52:55]
	v_mfma_f32_16x16x32_bf16 v[48:51], v[170:173], v[178:181], v[48:51]
	v_mfma_f32_16x16x32_bf16 v[36:39], v[162:165], v[186:189], v[36:39]
	v_mfma_f32_16x16x32_bf16 v[32:35], v[170:173], v[186:189], v[32:35]
	v_mfma_f32_16x16x32_bf16 v[20:23], v[162:165], v[204:207], v[20:23]
	v_mfma_f32_16x16x32_bf16 v[16:19], v[170:173], v[204:207], v[16:19]
	v_mfma_f32_16x16x32_bf16 v[4:7], v[162:165], v[212:215], v[4:7]
	v_mfma_f32_16x16x32_bf16 v[0:3], v[170:173], v[212:215], v[0:3]
	s_setprio 0
	s_barrier
	s_add_i32 s53, 0, 0x18000
	s_add_i32 s54, 0, 0x1c000
	v_add_u32_e32 v154, s53, v143
	v_add_u32_e32 v170, s54, v143
	ds_read_b128 v[138:141], v154
	ds_read_b128 v[146:149], v154 offset:1024
	ds_read_b128 v[150:153], v154 offset:2048
	ds_read_b128 v[154:157], v154 offset:3072
	ds_read_b128 v[158:161], v170
	ds_read_b128 v[162:165], v170 offset:1024
	ds_read_b128 v[166:169], v170 offset:2048
	ds_read_b128 v[170:173], v170 offset:3072
	s_add_u32 s26, s26, s12
	s_addc_u32 s27, s27, 0
	s_mov_b32 m0, s40
	v_lshl_add_u64 v[236:237], s[26:27], 0, v[128:129]
	ds_read_b128 v[174:177], v145 offset:32768
	ds_read_b128 v[178:181], v145 offset:33792
	ds_read_b128 v[182:185], v145 offset:34816
	ds_read_b128 v[186:189], v145 offset:35840
	ds_read_b128 v[200:203], v145 offset:36864
	ds_read_b128 v[204:207], v145 offset:37888
	ds_read_b128 v[208:211], v145 offset:38912
	ds_read_b128 v[212:215], v145 offset:39936
	global_load_lds_dwordx4 v[236:237], off
	s_mov_b32 m0, s41
	v_lshl_add_u64 v[236:237], s[26:27], 0, v[130:131]
	global_load_lds_dwordx4 v[236:237], off
	s_waitcnt vmcnt(8)
	s_waitcnt lgkmcnt(0)
	s_barrier
	s_setprio 1
	v_mfma_f32_16x16x32_bf16 v[124:127], v[138:141], v[174:177], v[124:127]
	v_mfma_f32_16x16x32_bf16 v[120:123], v[150:153], v[174:177], v[120:123]
	v_mfma_f32_16x16x32_bf16 v[108:111], v[138:141], v[182:185], v[108:111]
	v_mfma_f32_16x16x32_bf16 v[104:107], v[150:153], v[182:185], v[104:107]
	v_mfma_f32_16x16x32_bf16 v[92:95], v[138:141], v[200:203], v[92:95]
	v_mfma_f32_16x16x32_bf16 v[88:91], v[150:153], v[200:203], v[88:91]
	v_mfma_f32_16x16x32_bf16 v[76:79], v[138:141], v[208:211], v[76:79]
	v_mfma_f32_16x16x32_bf16 v[72:75], v[150:153], v[208:211], v[72:75]
	v_mfma_f32_16x16x32_bf16 v[124:127], v[146:149], v[178:181], v[124:127]
	v_mfma_f32_16x16x32_bf16 v[120:123], v[154:157], v[178:181], v[120:123]
	v_mfma_f32_16x16x32_bf16 v[108:111], v[146:149], v[186:189], v[108:111]
	v_mfma_f32_16x16x32_bf16 v[104:107], v[154:157], v[186:189], v[104:107]
	v_mfma_f32_16x16x32_bf16 v[92:95], v[146:149], v[204:207], v[92:95]
	v_mfma_f32_16x16x32_bf16 v[88:91], v[154:157], v[204:207], v[88:91]
	v_mfma_f32_16x16x32_bf16 v[76:79], v[146:149], v[212:215], v[76:79]
	v_mfma_f32_16x16x32_bf16 v[72:75], v[154:157], v[212:215], v[72:75]
	v_mfma_f32_16x16x32_bf16 v[116:119], v[158:161], v[174:177], v[116:119]
	v_mfma_f32_16x16x32_bf16 v[112:115], v[166:169], v[174:177], v[112:115]
	v_mfma_f32_16x16x32_bf16 v[100:103], v[158:161], v[182:185], v[100:103]
	v_mfma_f32_16x16x32_bf16 v[96:99], v[166:169], v[182:185], v[96:99]
	v_mfma_f32_16x16x32_bf16 v[84:87], v[158:161], v[200:203], v[84:87]
	v_mfma_f32_16x16x32_bf16 v[80:83], v[166:169], v[200:203], v[80:83]
	v_mfma_f32_16x16x32_bf16 v[68:71], v[158:161], v[208:211], v[68:71]
	v_mfma_f32_16x16x32_bf16 v[64:67], v[166:169], v[208:211], v[64:67]
	v_mfma_f32_16x16x32_bf16 v[116:119], v[162:165], v[178:181], v[116:119]
	v_mfma_f32_16x16x32_bf16 v[112:115], v[170:173], v[178:181], v[112:115]
	v_mfma_f32_16x16x32_bf16 v[100:103], v[162:165], v[186:189], v[100:103]
	v_mfma_f32_16x16x32_bf16 v[96:99], v[170:173], v[186:189], v[96:99]
	v_mfma_f32_16x16x32_bf16 v[84:87], v[162:165], v[204:207], v[84:87]
	v_mfma_f32_16x16x32_bf16 v[80:83], v[170:173], v[204:207], v[80:83]
	v_mfma_f32_16x16x32_bf16 v[68:71], v[162:165], v[212:215], v[68:71]
	v_mfma_f32_16x16x32_bf16 v[64:67], v[170:173], v[212:215], v[64:67]
	s_setprio 0
	s_barrier
; #define PG8_STAGE(bufoff, gbase, voff) do { _Pragma("unroll") for (int _i = 0; _i < 2; ++_i) \
;         __builtin_amdgcn_global_load_lds((const unsigned*)((const char*)(gbase) + (voff)[_i]), (PG8_LAS unsigned*)(lds + (bufoff) + ldsw + _i * 8192), 16, 0, 0); } while (0)
; #define PG8_LDA(dst, b, h) do { _Pragma("unroll") for (int m = 0; m < 4; ++m) _Pragma("unroll") for (int k = 0; k < 2; ++k) dst[m][k] = *(const PG8_LAS bf16x8*)(lds + PG8_SA(b, h) + aoff + m * 2048 + k * 1024); } while (0)
; #define PG8_MMA(ai, bj, At, Bt) do { __builtin_amdgcn_s_setprio(1); _Pragma("unroll") for (int m = 0; m < 4; ++m) _Pragma("unroll") for (int n = 0; n < 2; ++n) _Pragma("unroll") for (int k = 0; k < 2; ++k) \
;         acc[ai][bj][m][n] = __builtin_amdgcn_mfma_f32_16x16x32_bf16(Bt[n][k], At[m][k], acc[ai][bj][m][n], 0, 0, 0); __builtin_amdgcn_s_setprio(0); } while (0)
; #define PG8_WAIT_V(n) asm volatile("s_waitcnt vmcnt(" #n ")" ::: "memory")
; #define PG8_WAIT_L(n) asm volatile("s_waitcnt lgkmcnt(" #n ")" ::: "memory")
; #define PG8_BAR __builtin_amdgcn_s_barrier()
; #define PG8_SCHED __builtin_amdgcn_sched_barrier(0)
; template <class Epi, class Sched, bool ALIGN_EPI = false, bool SP2 = false>
; __device__ __forceinline__ void gemm_phase(PG8_LAS unsigned char* lds, const Gemm g, const Sched& S, const Epi& E, const int tid_in) {
;     ...
;             PG8_LDA(At, 1, 1); PG8_STAGE(PG8_SB(1, 0), b3, voffB); PG8_STAGE(PG8_SB(1, 1), b3 + hstep, voffB); PG8_STAGE(PG8_SA(1, 0), a3, voffA);
;             PG8_WAIT_V(8); PG8_WAIT_L(0); PG8_BAR; PG8_MMA(1, 0, At, B0); PG8_MMA(1, 1, At, B1); PG8_BAR; PG8_SCHED;
;     ...
;         if constexpr (ALIGN_EPI) { if (wr == 0) PG8_BAR; }
	s_add_i32 s26, s53, s35
	v_lshl_add_u64 v[190:191], v[190:191], 0, s[92:93]
	s_mov_b32 m0, s26
	ds_read_b128 v[174:177], v145 offset:49152
	ds_read_b128 v[178:181], v145 offset:50176
	ds_read_b128 v[182:185], v145 offset:51200
	ds_read_b128 v[186:189], v145 offset:52224
	ds_read_b128 v[200:203], v145 offset:53248
	ds_read_b128 v[204:207], v145 offset:54272
	ds_read_b128 v[208:211], v145 offset:55296
	ds_read_b128 v[212:215], v145 offset:56320
	global_load_lds_dwordx4 v[190:191], off
	v_lshl_add_u64 v[190:191], v[218:219], 0, s[92:93]
	s_add_i32 m0, s26, 0x2000
	s_add_i32 s26, s54, s35
	global_load_lds_dwordx4 v[190:191], off
	s_mov_b32 m0, s26
	v_lshl_add_u64 v[190:191], v[220:221], 0, s[92:93]
	global_load_lds_dwordx4 v[190:191], off
	s_add_i32 m0, s26, 0x2000
	v_lshl_add_u64 v[190:191], v[230:231], 0, s[92:93]
	global_load_lds_dwordx4 v[190:191], off
	s_mov_b32 m0, s42
	v_lshl_add_u64 v[190:191], v[232:233], 0, s[92:93]
	global_load_lds_dwordx4 v[190:191], off
	s_mov_b32 m0, s43
	v_lshl_add_u64 v[190:191], v[234:235], 0, s[92:93]
	global_load_lds_dwordx4 v[190:191], off
	s_waitcnt vmcnt(8)
	s_waitcnt lgkmcnt(0)
	s_barrier
	s_setprio 1
	v_mfma_f32_16x16x32_bf16 v[60:63], v[138:141], v[174:177], v[60:63]
	v_mfma_f32_16x16x32_bf16 v[56:59], v[150:153], v[174:177], v[56:59]
	v_mfma_f32_16x16x32_bf16 v[44:47], v[138:141], v[182:185], v[44:47]
	v_mfma_f32_16x16x32_bf16 v[40:43], v[150:153], v[182:185], v[40:43]
	v_mfma_f32_16x16x32_bf16 v[28:31], v[138:141], v[200:203], v[28:31]
	v_mfma_f32_16x16x32_bf16 v[24:27], v[150:153], v[200:203], v[24:27]
	v_mfma_f32_16x16x32_bf16 v[12:15], v[138:141], v[208:211], v[12:15]
	v_mfma_f32_16x16x32_bf16 v[8:11], v[150:153], v[208:211], v[8:11]
	v_mfma_f32_16x16x32_bf16 v[60:63], v[146:149], v[178:181], v[60:63]
	v_mfma_f32_16x16x32_bf16 v[56:59], v[154:157], v[178:181], v[56:59]
	v_mfma_f32_16x16x32_bf16 v[44:47], v[146:149], v[186:189], v[44:47]
	v_mfma_f32_16x16x32_bf16 v[40:43], v[154:157], v[186:189], v[40:43]
	v_mfma_f32_16x16x32_bf16 v[28:31], v[146:149], v[204:207], v[28:31]
	v_mfma_f32_16x16x32_bf16 v[24:27], v[154:157], v[204:207], v[24:27]
	v_mfma_f32_16x16x32_bf16 v[12:15], v[146:149], v[212:215], v[12:15]
	v_mfma_f32_16x16x32_bf16 v[8:11], v[154:157], v[212:215], v[8:11]
	v_mfma_f32_16x16x32_bf16 v[52:55], v[158:161], v[174:177], v[52:55]
	v_mfma_f32_16x16x32_bf16 v[48:51], v[166:169], v[174:177], v[48:51]
	v_mfma_f32_16x16x32_bf16 v[36:39], v[158:161], v[182:185], v[36:39]
	v_mfma_f32_16x16x32_bf16 v[32:35], v[166:169], v[182:185], v[32:35]
	v_mfma_f32_16x16x32_bf16 v[20:23], v[158:161], v[200:203], v[20:23]
	v_mfma_f32_16x16x32_bf16 v[16:19], v[166:169], v[200:203], v[16:19]
	v_mfma_f32_16x16x32_bf16 v[4:7], v[158:161], v[208:211], v[4:7]
	v_mfma_f32_16x16x32_bf16 v[0:3], v[166:169], v[208:211], v[0:3]
	v_mfma_f32_16x16x32_bf16 v[52:55], v[162:165], v[178:181], v[52:55]
	v_mfma_f32_16x16x32_bf16 v[48:51], v[170:173], v[178:181], v[48:51]
	v_mfma_f32_16x16x32_bf16 v[36:39], v[162:165], v[186:189], v[36:39]
	v_mfma_f32_16x16x32_bf16 v[32:35], v[170:173], v[186:189], v[32:35]
	v_mfma_f32_16x16x32_bf16 v[20:23], v[162:165], v[204:207], v[20:23]
	v_mfma_f32_16x16x32_bf16 v[16:19], v[170:173], v[204:207], v[16:19]
	v_mfma_f32_16x16x32_bf16 v[4:7], v[162:165], v[212:215], v[4:7]
	v_mfma_f32_16x16x32_bf16 v[0:3], v[170:173], v[212:215], v[0:3]
	s_setprio 0
	s_barrier
	s_add_u32 s24, s24, 0x100
	s_addc_u32 s25, s25, 0
	s_add_u32 s29, s29, 0x100
	s_addc_u32 s51, s51, 0
	s_cmp_ge_u32 s52, s50
	s_mov_b32 s26, s52
	s_cbranch_scc0 .LBB0_284
	s_and_b64 vcc, exec, s[16:17]
	s_cbranch_vccz .LBB0_287

; #define PG8_STAGE(bufoff, gbase, voff) do { _Pragma("unroll") for (int _i = 0; _i < 2; ++_i) \
;         __builtin_amdgcn_global_load_lds((const unsigned*)((const char*)(gbase) + (voff)[_i]), (PG8_LAS unsigned*)(lds + (bufoff) + ldsw + _i * 8192), 16, 0, 0); } while (0)
; #define PG8_LDA(dst, b, h) do { _Pragma("unroll") for (int m = 0; m < 4; ++m) _Pragma("unroll") for (int k = 0; k < 2; ++k) dst[m][k] = *(const PG8_LAS bf16x8*)(lds + PG8_SA(b, h) + aoff + m * 2048 + k * 1024); } while (0)
; #define PG8_LDB(dst, b, h) do { _Pragma("unroll") for (int n = 0; n < 2; ++n) _Pragma("unroll") for (int k = 0; k < 2; ++k) dst[n][k] = *(const PG8_LAS bf16x8*)(lds + PG8_SB(b, h) + boff + n * 2048 + k * 1024); } while (0)
; #define PG8_MMA(ai, bj, At, Bt) do { __builtin_amdgcn_s_setprio(1); _Pragma("unroll") for (int m = 0; m < 4; ++m) _Pragma("unroll") for (int n = 0; n < 2; ++n) _Pragma("unroll") for (int k = 0; k < 2; ++k) \
;         acc[ai][bj][m][n] = __builtin_amdgcn_mfma_f32_16x16x32_bf16(Bt[n][k], At[m][k], acc[ai][bj][m][n], 0, 0, 0); __builtin_amdgcn_s_setprio(0); } while (0)
; #define PG8_WAIT_V(n) asm volatile("s_waitcnt vmcnt(" #n ")" ::: "memory")
; #define PG8_WAIT_L(n) asm volatile("s_waitcnt lgkmcnt(" #n ")" ::: "memory")
; #define PG8_BAR __builtin_amdgcn_s_barrier()
; #define PG8_SCHED __builtin_amdgcn_sched_barrier(0)
; template <class Epi, class Sched, bool ALIGN_EPI = false, bool SP2 = false>
; __device__ __forceinline__ void gemm_phase(PG8_LAS unsigned char* lds, const Gemm g, const Sched& S, const Epi& E, const int tid_in) {
;     ...
;             PG8_LDB(B0, 0, 0); PG8_LDB(B1, 0, 1); PG8_SCHED; PG8_LDA(At, 0, 0); PG8_STAGE(PG8_SA(1, 1), a1 + hstep, voffA);
;             PG8_WAIT_V(8); PG8_WAIT_L(0); PG8_BAR; PG8_MMA(0, 0, At, B0); PG8_MMA(0, 1, At, B1); PG8_BAR; PG8_SCHED;
;             PG8_LDA(At, 0, 1); PG8_STAGE(PG8_SB(0, 0), b2, voffB); PG8_STAGE(PG8_SB(0, 1), b2 + hstep, voffB); PG8_STAGE(PG8_SA(0, 0), a2, voffA);
;             PG8_WAIT_V(8); PG8_WAIT_L(0); PG8_BAR; PG8_MMA(1, 0, At, B0); PG8_MMA(1, 1, At, B1); PG8_BAR; PG8_SCHED;
.LBB0_307:
	s_add_u32 s20, s4, 0xfffc0080
	s_addc_u32 s21, s5, -1
	s_add_i32 s44, 0, 0x10000
	s_cmp_eq_u32 s43, 12
	s_cselect_b32 s23, s11, s21
	s_cselect_b32 s22, s39, s20
	s_cselect_b32 s21, s9, s42
	s_cselect_b32 s20, s40, s41
	s_add_i32 s46, 0, 0x14000
	v_add_u32_e32 v154, s44, v143
	v_add_u32_e32 v170, s46, v143
	ds_read_b128 v[138:141], v154
	ds_read_b128 v[146:149], v154 offset:1024
	ds_read_b128 v[150:153], v154 offset:2048
	ds_read_b128 v[154:157], v154 offset:3072
	ds_read_b128 v[158:161], v170
	ds_read_b128 v[162:165], v170 offset:1024
	ds_read_b128 v[166:169], v170 offset:2048
	ds_read_b128 v[170:173], v170 offset:3072
	v_lshl_add_u64 v[190:191], s[4:5], 0, v[134:135]
	s_add_i32 m0, s30, 0xc000
	ds_read_b128 v[174:177], v145
	ds_read_b128 v[178:181], v145 offset:1024
	ds_read_b128 v[182:185], v145 offset:2048
	ds_read_b128 v[186:189], v145 offset:3072
	ds_read_b128 v[200:203], v145 offset:4096
	ds_read_b128 v[204:207], v145 offset:5120
	ds_read_b128 v[208:211], v145 offset:6144
	ds_read_b128 v[212:215], v145 offset:7168
	global_load_lds_dwordx4 v[190:191], off
	s_add_i32 m0, s30, 0xe000
	v_lshl_add_u64 v[190:191], s[4:5], 0, v[136:137]
	global_load_lds_dwordx4 v[190:191], off
	s_waitcnt vmcnt(8)
	s_waitcnt lgkmcnt(0)
	s_barrier
	s_setprio 1
	v_mfma_f32_16x16x32_bf16 v[124:127], v[138:141], v[174:177], v[124:127]
	v_mfma_f32_16x16x32_bf16 v[116:119], v[150:153], v[174:177], v[116:119]
	v_mfma_f32_16x16x32_bf16 v[108:111], v[138:141], v[182:185], v[108:111]
	v_mfma_f32_16x16x32_bf16 v[100:103], v[150:153], v[182:185], v[100:103]
	v_mfma_f32_16x16x32_bf16 v[92:95], v[138:141], v[200:203], v[92:95]
	v_mfma_f32_16x16x32_bf16 v[84:87], v[150:153], v[200:203], v[84:87]
	v_mfma_f32_16x16x32_bf16 v[76:79], v[138:141], v[208:211], v[76:79]
	v_mfma_f32_16x16x32_bf16 v[68:71], v[150:153], v[208:211], v[68:71]
	v_mfma_f32_16x16x32_bf16 v[124:127], v[146:149], v[178:181], v[124:127]
	v_mfma_f32_16x16x32_bf16 v[116:119], v[154:157], v[178:181], v[116:119]
	v_mfma_f32_16x16x32_bf16 v[108:111], v[146:149], v[186:189], v[108:111]
	v_mfma_f32_16x16x32_bf16 v[100:103], v[154:157], v[186:189], v[100:103]
	v_mfma_f32_16x16x32_bf16 v[92:95], v[146:149], v[204:207], v[92:95]
	v_mfma_f32_16x16x32_bf16 v[84:87], v[154:157], v[204:207], v[84:87]
	v_mfma_f32_16x16x32_bf16 v[76:79], v[146:149], v[212:215], v[76:79]
	v_mfma_f32_16x16x32_bf16 v[68:71], v[154:157], v[212:215], v[68:71]
	v_mfma_f32_16x16x32_bf16 v[120:123], v[158:161], v[174:177], v[120:123]
	v_mfma_f32_16x16x32_bf16 v[112:115], v[166:169], v[174:177], v[112:115]
	v_mfma_f32_16x16x32_bf16 v[104:107], v[158:161], v[182:185], v[104:107]
	v_mfma_f32_16x16x32_bf16 v[96:99], v[166:169], v[182:185], v[96:99]
	v_mfma_f32_16x16x32_bf16 v[88:91], v[158:161], v[200:203], v[88:91]
	v_mfma_f32_16x16x32_bf16 v[80:83], v[166:169], v[200:203], v[80:83]
	v_mfma_f32_16x16x32_bf16 v[72:75], v[158:161], v[208:211], v[72:75]
	v_mfma_f32_16x16x32_bf16 v[64:67], v[166:169], v[208:211], v[64:67]
	v_mfma_f32_16x16x32_bf16 v[120:123], v[162:165], v[178:181], v[120:123]
	v_mfma_f32_16x16x32_bf16 v[112:115], v[170:173], v[178:181], v[112:115]
	v_mfma_f32_16x16x32_bf16 v[104:107], v[162:165], v[186:189], v[104:107]
	v_mfma_f32_16x16x32_bf16 v[96:99], v[170:173], v[186:189], v[96:99]
	v_mfma_f32_16x16x32_bf16 v[88:91], v[162:165], v[204:207], v[88:91]
	v_mfma_f32_16x16x32_bf16 v[80:83], v[170:173], v[204:207], v[80:83]
	v_mfma_f32_16x16x32_bf16 v[72:75], v[162:165], v[212:215], v[72:75]
	v_mfma_f32_16x16x32_bf16 v[64:67], v[170:173], v[212:215], v[64:67]
	s_setprio 0
	s_barrier
	s_add_i32 s44, s44, s27
	v_lshl_add_u64 v[190:191], s[20:21], 0, v[192:193]
	s_mov_b32 m0, s44
	ds_read_b128 v[174:177], v145 offset:16384
	ds_read_b128 v[178:181], v145 offset:17408
	ds_read_b128 v[182:185], v145 offset:18432
	ds_read_b128 v[186:189], v145 offset:19456
	ds_read_b128 v[200:203], v145 offset:20480
	ds_read_b128 v[204:207], v145 offset:21504
	ds_read_b128 v[208:211], v145 offset:22528
	ds_read_b128 v[212:215], v145 offset:23552
	global_load_lds_dwordx4 v[190:191], off
	s_add_i32 m0, s44, 0x2000
	s_add_u32 s44, s20, 0x40000
	v_lshl_add_u64 v[218:219], s[20:21], 0, v[128:129]
	s_addc_u32 s45, s21, 0
	s_add_i32 s46, s46, s27
	global_load_lds_dwordx4 v[218:219], off
	v_lshl_add_u64 v[220:221], s[44:45], 0, v[192:193]
	s_mov_b32 m0, s46
	v_lshl_add_u64 v[230:231], s[22:23], 0, v[130:131]
	global_load_lds_dwordx4 v[220:221], off
	s_add_i32 m0, s46, 0x2000
	v_lshl_add_u64 v[220:221], s[44:45], 0, v[128:129]
	global_load_lds_dwordx4 v[220:221], off
	s_mov_b32 m0, s30
	v_lshl_add_u64 v[220:221], s[22:23], 0, v[132:133]
	global_load_lds_dwordx4 v[220:221], off
	s_mov_b32 m0, s31
	s_nop 0
	global_load_lds_dwordx4 v[230:231], off
	s_waitcnt vmcnt(8)
	s_waitcnt lgkmcnt(0)
	s_barrier
; #define PG8_STAGE(bufoff, gbase, voff) do { _Pragma("unroll") for (int _i = 0; _i < 2; ++_i) \
;         __builtin_amdgcn_global_load_lds((const unsigned*)((const char*)(gbase) + (voff)[_i]), (PG8_LAS unsigned*)(lds + (bufoff) + ldsw + _i * 8192), 16, 0, 0); } while (0)
; #define PG8_LDA(dst, b, h) do { _Pragma("unroll") for (int m = 0; m < 4; ++m) _Pragma("unroll") for (int k = 0; k < 2; ++k) dst[m][k] = *(const PG8_LAS bf16x8*)(lds + PG8_SA(b, h) + aoff + m * 2048 + k * 1024); } while (0)
; #define PG8_LDB(dst, b, h) do { _Pragma("unroll") for (int n = 0; n < 2; ++n) _Pragma("unroll") for (int k = 0; k < 2; ++k) dst[n][k] = *(const PG8_LAS bf16x8*)(lds + PG8_SB(b, h) + boff + n * 2048 + k * 1024); } while (0)
; #define PG8_MMA(ai, bj, At, Bt) do { __builtin_amdgcn_s_setprio(1); _Pragma("unroll") for (int m = 0; m < 4; ++m) _Pragma("unroll") for (int n = 0; n < 2; ++n) _Pragma("unroll") for (int k = 0; k < 2; ++k) \
;         acc[ai][bj][m][n] = __builtin_amdgcn_mfma_f32_16x16x32_bf16(Bt[n][k], At[m][k], acc[ai][bj][m][n], 0, 0, 0); __builtin_amdgcn_s_setprio(0); } while (0)
; #define PG8_WAIT_V(n) asm volatile("s_waitcnt vmcnt(" #n ")" ::: "memory")
; #define PG8_WAIT_L(n) asm volatile("s_waitcnt lgkmcnt(" #n ")" ::: "memory")
; #define PG8_BAR __builtin_amdgcn_s_barrier()
; #define PG8_SCHED __builtin_amdgcn_sched_barrier(0)
; template <class Epi, class Sched, bool ALIGN_EPI = false, bool SP2 = false>
; __device__ __forceinline__ void gemm_phase(PG8_LAS unsigned char* lds, const Gemm g, const Sched& S, const Epi& E, const int tid_in) {
;     ...
;             PG8_WAIT_V(8); PG8_WAIT_L(0); PG8_BAR; PG8_MMA(1, 0, At, B0); PG8_MMA(1, 1, At, B1); PG8_BAR; PG8_SCHED;
;             PG8_LDB(B0, 1, 0); PG8_LDB(B1, 1, 1); PG8_SCHED; PG8_LDA(At, 1, 0); PG8_STAGE(PG8_SA(0, 1), a2 + hstep, voffA);
;             PG8_WAIT_V(8); PG8_WAIT_L(0); PG8_BAR; PG8_MMA(0, 0, At, B0); PG8_MMA(0, 1, At, B1); PG8_BAR; PG8_SCHED;
	s_setprio 1
	v_mfma_f32_16x16x32_bf16 v[60:63], v[138:141], v[174:177], v[60:63]
	v_mfma_f32_16x16x32_bf16 v[52:55], v[150:153], v[174:177], v[52:55]
	v_mfma_f32_16x16x32_bf16 v[44:47], v[138:141], v[182:185], v[44:47]
	v_mfma_f32_16x16x32_bf16 v[36:39], v[150:153], v[182:185], v[36:39]
	v_mfma_f32_16x16x32_bf16 v[28:31], v[138:141], v[200:203], v[28:31]
	v_mfma_f32_16x16x32_bf16 v[20:23], v[150:153], v[200:203], v[20:23]
	v_mfma_f32_16x16x32_bf16 v[12:15], v[138:141], v[208:211], v[12:15]
	v_mfma_f32_16x16x32_bf16 v[4:7], v[150:153], v[208:211], v[4:7]
	v_mfma_f32_16x16x32_bf16 v[60:63], v[146:149], v[178:181], v[60:63]
	v_mfma_f32_16x16x32_bf16 v[52:55], v[154:157], v[178:181], v[52:55]
	v_mfma_f32_16x16x32_bf16 v[44:47], v[146:149], v[186:189], v[44:47]
	v_mfma_f32_16x16x32_bf16 v[36:39], v[154:157], v[186:189], v[36:39]
	v_mfma_f32_16x16x32_bf16 v[28:31], v[146:149], v[204:207], v[28:31]
	v_mfma_f32_16x16x32_bf16 v[20:23], v[154:157], v[204:207], v[20:23]
	v_mfma_f32_16x16x32_bf16 v[12:15], v[146:149], v[212:215], v[12:15]
	v_mfma_f32_16x16x32_bf16 v[4:7], v[154:157], v[212:215], v[4:7]
	v_mfma_f32_16x16x32_bf16 v[56:59], v[158:161], v[174:177], v[56:59]
	v_mfma_f32_16x16x32_bf16 v[48:51], v[166:169], v[174:177], v[48:51]
	v_mfma_f32_16x16x32_bf16 v[40:43], v[158:161], v[182:185], v[40:43]
	v_mfma_f32_16x16x32_bf16 v[32:35], v[166:169], v[182:185], v[32:35]
	v_mfma_f32_16x16x32_bf16 v[24:27], v[158:161], v[200:203], v[24:27]
	v_mfma_f32_16x16x32_bf16 v[16:19], v[166:169], v[200:203], v[16:19]
	v_mfma_f32_16x16x32_bf16 v[8:11], v[158:161], v[208:211], v[8:11]
	v_mfma_f32_16x16x32_bf16 v[0:3], v[166:169], v[208:211], v[0:3]
	v_mfma_f32_16x16x32_bf16 v[56:59], v[162:165], v[178:181], v[56:59]
	v_mfma_f32_16x16x32_bf16 v[48:51], v[170:173], v[178:181], v[48:51]
	v_mfma_f32_16x16x32_bf16 v[40:43], v[162:165], v[186:189], v[40:43]
	v_mfma_f32_16x16x32_bf16 v[32:35], v[170:173], v[186:189], v[32:35]
	v_mfma_f32_16x16x32_bf16 v[24:27], v[162:165], v[204:207], v[24:27]
	v_mfma_f32_16x16x32_bf16 v[16:19], v[170:173], v[204:207], v[16:19]
	v_mfma_f32_16x16x32_bf16 v[8:11], v[162:165], v[212:215], v[8:11]
	v_mfma_f32_16x16x32_bf16 v[0:3], v[170:173], v[212:215], v[0:3]
	s_setprio 0
	s_barrier
	s_add_i32 s44, 0, 0x18000
	s_add_i32 s45, 0, 0x1c000
	v_add_u32_e32 v154, s44, v143
	v_add_u32_e32 v170, s45, v143
	ds_read_b128 v[138:141], v154
	ds_read_b128 v[146:149], v154 offset:1024
	ds_read_b128 v[150:153], v154 offset:2048
	ds_read_b128 v[154:157], v154 offset:3072
	ds_read_b128 v[158:161], v170
	ds_read_b128 v[162:165], v170 offset:1024
	ds_read_b128 v[166:169], v170 offset:2048
	ds_read_b128 v[170:173], v170 offset:3072
	s_add_u32 s22, s22, 0x40000
	s_addc_u32 s23, s23, 0
	s_mov_b32 m0, s34
	v_lshl_add_u64 v[232:233], s[22:23], 0, v[132:133]
	ds_read_b128 v[174:177], v145 offset:32768
	ds_read_b128 v[178:181], v145 offset:33792
	ds_read_b128 v[182:185], v145 offset:34816
	ds_read_b128 v[186:189], v145 offset:35840
	ds_read_b128 v[200:203], v145 offset:36864
	ds_read_b128 v[204:207], v145 offset:37888
	ds_read_b128 v[208:211], v145 offset:38912
	ds_read_b128 v[212:215], v145 offset:39936
	global_load_lds_dwordx4 v[232:233], off
	s_mov_b32 m0, s35
	v_lshl_add_u64 v[232:233], s[22:23], 0, v[130:131]
	global_load_lds_dwordx4 v[232:233], off
	s_waitcnt vmcnt(8)
	s_waitcnt lgkmcnt(0)
	s_barrier
	s_setprio 1
	v_mfma_f32_16x16x32_bf16 v[124:127], v[138:141], v[174:177], v[124:127]
	v_mfma_f32_16x16x32_bf16 v[116:119], v[150:153], v[174:177], v[116:119]
	v_mfma_f32_16x16x32_bf16 v[108:111], v[138:141], v[182:185], v[108:111]
	v_mfma_f32_16x16x32_bf16 v[100:103], v[150:153], v[182:185], v[100:103]
	v_mfma_f32_16x16x32_bf16 v[92:95], v[138:141], v[200:203], v[92:95]
	v_mfma_f32_16x16x32_bf16 v[84:87], v[150:153], v[200:203], v[84:87]
	v_mfma_f32_16x16x32_bf16 v[76:79], v[138:141], v[208:211], v[76:79]
	v_mfma_f32_16x16x32_bf16 v[68:71], v[150:153], v[208:211], v[68:71]
	v_mfma_f32_16x16x32_bf16 v[124:127], v[146:149], v[178:181], v[124:127]
	v_mfma_f32_16x16x32_bf16 v[116:119], v[154:157], v[178:181], v[116:119]
	v_mfma_f32_16x16x32_bf16 v[108:111], v[146:149], v[186:189], v[108:111]
	v_mfma_f32_16x16x32_bf16 v[100:103], v[154:157], v[186:189], v[100:103]
	v_mfma_f32_16x16x32_bf16 v[92:95], v[146:149], v[204:207], v[92:95]
	v_mfma_f32_16x16x32_bf16 v[84:87], v[154:157], v[204:207], v[84:87]
	v_mfma_f32_16x16x32_bf16 v[76:79], v[146:149], v[212:215], v[76:79]
	v_mfma_f32_16x16x32_bf16 v[68:71], v[154:157], v[212:215], v[68:71]
	v_mfma_f32_16x16x32_bf16 v[120:123], v[158:161], v[174:177], v[120:123]
	v_mfma_f32_16x16x32_bf16 v[112:115], v[166:169], v[174:177], v[112:115]
	v_mfma_f32_16x16x32_bf16 v[104:107], v[158:161], v[182:185], v[104:107]
	v_mfma_f32_16x16x32_bf16 v[96:99], v[166:169], v[182:185], v[96:99]
	v_mfma_f32_16x16x32_bf16 v[88:91], v[158:161], v[200:203], v[88:91]
	v_mfma_f32_16x16x32_bf16 v[80:83], v[166:169], v[200:203], v[80:83]
	v_mfma_f32_16x16x32_bf16 v[72:75], v[158:161], v[208:211], v[72:75]
	v_mfma_f32_16x16x32_bf16 v[64:67], v[166:169], v[208:211], v[64:67]
	v_mfma_f32_16x16x32_bf16 v[120:123], v[162:165], v[178:181], v[120:123]
	v_mfma_f32_16x16x32_bf16 v[112:115], v[170:173], v[178:181], v[112:115]
	v_mfma_f32_16x16x32_bf16 v[104:107], v[162:165], v[186:189], v[104:107]
	v_mfma_f32_16x16x32_bf16 v[96:99], v[170:173], v[186:189], v[96:99]
	v_mfma_f32_16x16x32_bf16 v[88:91], v[162:165], v[204:207], v[88:91]
	v_mfma_f32_16x16x32_bf16 v[80:83], v[170:173], v[204:207], v[80:83]
	v_mfma_f32_16x16x32_bf16 v[72:75], v[162:165], v[212:215], v[72:75]
	v_mfma_f32_16x16x32_bf16 v[64:67], v[170:173], v[212:215], v[64:67]
	s_setprio 0
	s_barrier
; #define PG8_STAGE(bufoff, gbase, voff) do { _Pragma("unroll") for (int _i = 0; _i < 2; ++_i) \
;         __builtin_amdgcn_global_load_lds((const unsigned*)((const char*)(gbase) + (voff)[_i]), (PG8_LAS unsigned*)(lds + (bufoff) + ldsw + _i * 8192), 16, 0, 0); } while (0)
; #define PG8_LDA(dst, b, h) do { _Pragma("unroll") for (int m = 0; m < 4; ++m) _Pragma("unroll") for (int k = 0; k < 2; ++k) dst[m][k] = *(const PG8_LAS bf16x8*)(lds + PG8_SA(b, h) + aoff + m * 2048 + k * 1024); } while (0)
; #define PG8_MMA(ai, bj, At, Bt) do { __builtin_amdgcn_s_setprio(1); _Pragma("unroll") for (int m = 0; m < 4; ++m) _Pragma("unroll") for (int n = 0; n < 2; ++n) _Pragma("unroll") for (int k = 0; k < 2; ++k) \
;         acc[ai][bj][m][n] = __builtin_amdgcn_mfma_f32_16x16x32_bf16(Bt[n][k], At[m][k], acc[ai][bj][m][n], 0, 0, 0); __builtin_amdgcn_s_setprio(0); } while (0)
; #define PG8_WAIT_V(n) asm volatile("s_waitcnt vmcnt(" #n ")" ::: "memory")
; #define PG8_WAIT_L(n) asm volatile("s_waitcnt lgkmcnt(" #n ")" ::: "memory")
; #define PG8_BAR __builtin_amdgcn_s_barrier()
; #define PG8_SCHED __builtin_amdgcn_sched_barrier(0)
; template <class Epi, class Sched, bool ALIGN_EPI = false, bool SP2 = false>
; __device__ __forceinline__ void gemm_phase(PG8_LAS unsigned char* lds, const Gemm g, const Sched& S, const Epi& E, const int tid_in) {
;     ...
;             PG8_LDA(At, 1, 1); PG8_STAGE(PG8_SB(1, 0), b3, voffB); PG8_STAGE(PG8_SB(1, 1), b3 + hstep, voffB); PG8_STAGE(PG8_SA(1, 0), a3, voffA);
;             PG8_WAIT_V(8); PG8_WAIT_L(0); PG8_BAR; PG8_MMA(1, 0, At, B0); PG8_MMA(1, 1, At, B1); PG8_BAR; PG8_SCHED;
;     ...
;         if constexpr (ALIGN_EPI) { if (wr == 0) PG8_BAR; }
	s_add_i32 s22, s44, s27
	v_lshl_add_u64 v[190:191], v[190:191], 0, s[92:93]
	s_mov_b32 m0, s22
	ds_read_b128 v[174:177], v145 offset:49152
	ds_read_b128 v[178:181], v145 offset:50176
	ds_read_b128 v[182:185], v145 offset:51200
	ds_read_b128 v[186:189], v145 offset:52224
	ds_read_b128 v[200:203], v145 offset:53248
	ds_read_b128 v[204:207], v145 offset:54272
	ds_read_b128 v[208:211], v145 offset:55296
	ds_read_b128 v[212:215], v145 offset:56320
	global_load_lds_dwordx4 v[190:191], off
	s_add_i32 m0, s22, 0x2000
	s_add_u32 s20, s20, 0x40080
	v_lshl_add_u64 v[190:191], v[218:219], 0, s[92:93]
	s_addc_u32 s21, s21, 0
	s_add_i32 s22, s45, s27
	global_load_lds_dwordx4 v[190:191], off
	s_mov_b32 m0, s22
	v_lshl_add_u64 v[190:191], s[20:21], 0, v[192:193]
	global_load_lds_dwordx4 v[190:191], off
	s_add_i32 m0, s22, 0x2000
	v_lshl_add_u64 v[190:191], s[20:21], 0, v[128:129]
	global_load_lds_dwordx4 v[190:191], off
	s_mov_b32 m0, s36
	v_lshl_add_u64 v[190:191], v[220:221], 0, s[92:93]
	global_load_lds_dwordx4 v[190:191], off
	s_mov_b32 m0, s37
	v_lshl_add_u64 v[190:191], v[230:231], 0, s[92:93]
	global_load_lds_dwordx4 v[190:191], off
	s_waitcnt vmcnt(8)
	s_waitcnt lgkmcnt(0)
	s_barrier
	s_setprio 1
	v_mfma_f32_16x16x32_bf16 v[60:63], v[138:141], v[174:177], v[60:63]
	v_mfma_f32_16x16x32_bf16 v[52:55], v[150:153], v[174:177], v[52:55]
	v_mfma_f32_16x16x32_bf16 v[44:47], v[138:141], v[182:185], v[44:47]
	v_mfma_f32_16x16x32_bf16 v[36:39], v[150:153], v[182:185], v[36:39]
	v_mfma_f32_16x16x32_bf16 v[28:31], v[138:141], v[200:203], v[28:31]
	v_mfma_f32_16x16x32_bf16 v[20:23], v[150:153], v[200:203], v[20:23]
	v_mfma_f32_16x16x32_bf16 v[12:15], v[138:141], v[208:211], v[12:15]
	v_mfma_f32_16x16x32_bf16 v[4:7], v[150:153], v[208:211], v[4:7]
	v_mfma_f32_16x16x32_bf16 v[60:63], v[146:149], v[178:181], v[60:63]
	v_mfma_f32_16x16x32_bf16 v[52:55], v[154:157], v[178:181], v[52:55]
	v_mfma_f32_16x16x32_bf16 v[44:47], v[146:149], v[186:189], v[44:47]
	v_mfma_f32_16x16x32_bf16 v[36:39], v[154:157], v[186:189], v[36:39]
	v_mfma_f32_16x16x32_bf16 v[28:31], v[146:149], v[204:207], v[28:31]
	v_mfma_f32_16x16x32_bf16 v[20:23], v[154:157], v[204:207], v[20:23]
	v_mfma_f32_16x16x32_bf16 v[12:15], v[146:149], v[212:215], v[12:15]
	v_mfma_f32_16x16x32_bf16 v[4:7], v[154:157], v[212:215], v[4:7]
	v_mfma_f32_16x16x32_bf16 v[56:59], v[158:161], v[174:177], v[56:59]
	v_mfma_f32_16x16x32_bf16 v[48:51], v[166:169], v[174:177], v[48:51]
	v_mfma_f32_16x16x32_bf16 v[40:43], v[158:161], v[182:185], v[40:43]
	v_mfma_f32_16x16x32_bf16 v[32:35], v[166:169], v[182:185], v[32:35]
	v_mfma_f32_16x16x32_bf16 v[24:27], v[158:161], v[200:203], v[24:27]
	v_mfma_f32_16x16x32_bf16 v[16:19], v[166:169], v[200:203], v[16:19]
	v_mfma_f32_16x16x32_bf16 v[8:11], v[158:161], v[208:211], v[8:11]
	v_mfma_f32_16x16x32_bf16 v[0:3], v[166:169], v[208:211], v[0:3]
	v_mfma_f32_16x16x32_bf16 v[56:59], v[162:165], v[178:181], v[56:59]
	v_mfma_f32_16x16x32_bf16 v[48:51], v[170:173], v[178:181], v[48:51]
	v_mfma_f32_16x16x32_bf16 v[40:43], v[162:165], v[186:189], v[40:43]
	v_mfma_f32_16x16x32_bf16 v[32:35], v[170:173], v[186:189], v[32:35]
	v_mfma_f32_16x16x32_bf16 v[24:27], v[162:165], v[204:207], v[24:27]
	v_mfma_f32_16x16x32_bf16 v[16:19], v[170:173], v[204:207], v[16:19]
	v_mfma_f32_16x16x32_bf16 v[8:11], v[162:165], v[212:215], v[8:11]
	v_mfma_f32_16x16x32_bf16 v[0:3], v[170:173], v[212:215], v[0:3]
	s_setprio 0
	s_barrier
	s_add_i32 s43, s43, 2
	s_add_u32 s4, s4, 0x100
	s_addc_u32 s5, s5, 0
	s_add_u32 s41, s41, 0x100
	s_addc_u32 s42, s42, 0
	s_cmp_gt_u32 s43, 13
	s_cbranch_scc0 .LBB0_307
	s_and_b64 vcc, exec, s[18:19]
	s_cbranch_vccz .LBB0_310
	s_barrier
